# v65: grid barrier between a folded residual step and the GEMM that consumes its bf16 rows replaced by a wait on the 6 panel counters of the workgroup's own XCD group
# baseline (speedup 1.0000x reference)
.LBB0_9:
	s_mul_i32 s3, s6, 3
	s_getpc_b64 s[0:1]
	s_add_u32 s0, s0, PROG@rel32@lo+4
	s_addc_u32 s1, s1, PROG@rel32@hi+12
	s_and_b32 s2, s3, -4
	s_add_u32 s0, s0, s2
	s_addc_u32 s1, s1, 0
	s_load_dwordx2 s[0:1], s[0:1], 0x0
	s_and_b32 s3, s3, 3
	s_lshl_b32 s3, s3, 3
	s_waitcnt lgkmcnt(0)
	s_lshr_b64 s[0:1], s[0:1], s3
	s_and_b32 s2, s0, 0xffff
	v_mov_b32_e32 v0, s2
	s_bfe_u32 s2, s0, 0x80010
	v_mov_b32_e32 v2, s2
	s_and_b32 s8, s0, 0xff
	s_cmp_eq_u32 s6, 0
	s_cbranch_scc1 .Lxl_done
	s_cmp_eq_u32 s8, 1
	s_cbranch_scc1 .Lxl_done
	v_readlane_b32 s2, v255, 0
	s_cmp_lg_u32 s2, 0
	s_cbranch_scc1 .Lxl_done
	v_readlane_b32 s2, v255, 11
	s_cmp_eq_u32 s2, 4
	s_cselect_b32 s3, 1, 0
	s_cmp_eq_u32 s2, 8
	s_cselect_b32 s3, 1, s3
	s_cmp_eq_u32 s3, 0
	s_cbranch_scc1 .Lxl_done
	v_readlane_b32 s2, v254, 4
	s_cmp_lg_u32 s2, 0
	s_cbranch_scc1 .Lxl_bar
	v_readlane_b32 s0, v254, 39
	v_readlane_b32 s1, v254, 40
	s_add_i32 s2, s6, -1
	s_lshl_b32 s2, s2, 8
	s_and_b32 s3, s66, 7
	s_mul_i32 s3, s3, 24
	s_add_i32 s2, s2, s3
	s_add_i32 s2, s2, 0x10000
	s_add_u32 s0, s0, s2
	s_addc_u32 s1, s1, 0
	s_mov_b32 s2, 0
.Lxl_poll:
	global_load_dwordx4 v[4:7], v1, s[0:1] sc1
	global_load_dwordx2 v[8:9], v1, s[0:1] offset:16 sc1
	s_waitcnt vmcnt(0)
	v_min_u32_e32 v4, v4, v5
	v_min_u32_e32 v6, v6, v7
	v_min_u32_e32 v8, v8, v9
	v_min3_u32 v4, v4, v6, v8
	s_nop 0
	v_readfirstlane_b32 s3, v4
	s_cmp_ge_u32 s3, 8
	s_cbranch_scc1 .Lxl_ok
	s_add_i32 s2, s2, 1
	s_cmp_gt_u32 s2, 0x20000
	s_cbranch_scc1 .Lxl_ok
	s_sleep 1
	s_branch .Lxl_poll

.Lxl_done:
	s_cmp_gt_u32 s6, 1
	s_cbranch_scc1 .Lsm_done
	v_readlane_b32 s0, v254, 39
	v_readlane_b32 s1, v254, 40
	s_add_u32 s0, s0, 0xc000
	s_addc_u32 s1, s1, 0
	s_cmp_eq_u32 s6, 1
	s_cbranch_scc1 .Lsm_cache
	s_getreg_b32 s2, hwreg(HW_REG_XCC_ID, 0, 4)
	s_and_b32 s2, s2, 15
	s_lshl_b32 s2, 1, s2
	s_and_b32 s3, s66, 7
	s_lshl_b32 s3, s3, 2
	s_add_u32 s0, s0, s3
	s_addc_u32 s1, s1, 0
	v_mov_b32_e32 v3, s2
	s_mov_b64 s[2:3], exec
	s_mov_b64 exec, 1
	global_atomic_or v1, v3, s[0:1]
	s_mov_b64 exec, s[2:3]
	s_branch .Lsm_done
	s_nop 0
	s_nop 0
	s_nop 0
	s_nop 0
	s_nop 0
	s_nop 0
	s_nop 0
	s_nop 0
	s_nop 0
	s_nop 0
	s_nop 0

PROG:
	.byte	0, 0, 1
	.byte	1, 0, 1
	.byte	3, 0, 1
	.byte	4, 0, 1
	.byte	1, 1, 1
	.byte	5, 0, 1
	.byte	6, 0, 1
	.byte	7, 0, 1
	.byte	8, 0, 0
	.byte	3, 1, 1
	.byte	4, 1, 0
	.byte	3, 2, 1
	.byte	4, 2, 1
	.byte	2, 5, 1
	.byte	9, 0, 0
	.byte	10, 0, 1
	.byte	11, 0, 1
	.byte	8, 1, 0
	.byte	1, 6, 1
	.byte	3, 3, 1
	.byte	4, 3, 0
	.byte	3, 4, 1
	.byte	4, 4, 0
	.byte	12, 0, 1
	.byte	13, 0, 1
	.byte	14, 0, 1
	.byte	8, 2, 0
	.byte	3, 5, 1
	.byte	4, 5, 0
	.byte	3, 6, 1
	.byte	4, 6, 0
	.byte	15, 0, 1
	.byte	16, 0, 1
	.byte	8, 3, 0
	.byte	3, 7, 1
	.byte	4, 7, 0
	.size	PROG, 108

	.protected	BGTAB
	.type	BGTAB,@object
	.globl	BGTAB
	.p2align	4, 0x0
